# v27b + B1: the LoRA weight table (884 KB, read by every workgroup) is pulled into each XCD's L2 by a cooperative prefetch during the staging step
# baseline (speedup 1.0000x reference)
; __device__ __forceinline__ void phase_b1(const P& p, const Ctx& c, int seg) {
;     ...
;     for (int it = c.bid; it < MS / 16; it += c.G) {
;         const int r0 = it * 16, b = r0 >> 9, tl0 = r0 & 511;
;         __syncthreads();
;         for (int e = c.tid; e < 16 * 288; e += 512) { const int row = e / 288, cc = e % 288, col = 4608 + cc;
.LBB0_715:
	s_lshl_b32 s35, s34, 4
	s_ashr_i32 s8, s34, 5
	s_and_b32 s9, s35, 0x1f0
	s_mul_hi_i32 s10, s8, 0x2640
	s_mul_i32 s11, s8, 0x2640
	s_barrier
	s_mov_b64 s[12:13], exec
	v_readlane_b32 s14, v255, 46
	v_readlane_b32 s15, v255, 47
	s_and_b64 s[14:15], s[12:13], s[14:15]
	s_mov_b64 exec, s[14:15]
	s_cbranch_execz .LBB0_728
; __device__ __forceinline__ float bf2f(bf16_t b) { return __uint_as_float(((unsigned)b) << 16); }
; __device__ __forceinline__ void phase_b1(const P& p, const Ctx& c, int seg) {
;     ...
;         for (int e = c.tid; e < 16 * 288; e += 512) { const int row = e / 288, cc = e % 288, col = 4608 + cc;
;             const float cur = bf2f(P1[(size_t)(r0 + row) * P1W + col]);
;             float prev = 0.f; if (tl0 + row > 0) prev = bf2f(P1[(size_t)(r0 + row - 1) * P1W + col]); else if (seg > 0) prev = bf2f(PTr[(size_t)b * RW_SHIFT + col]);
;             const float pv = cur + p.rw_mu[col] * (prev - cur);
	v_readlane_b32 s14, v255, 43
	s_add_u32 s14, s14, s11
	v_readlane_b32 s15, v255, 45
	s_addc_u32 s15, s15, s10
	s_mov_b32 s39, 0x38e38e39
	s_movk_i32 s40, 0x2800
	s_lshr_b32 s16, s34, 3
	s_lshl_b32 s16, s16, 9
	v_add_u32_e32 v90, s16, v138
	v_lshlrev_b32_e32 v90, 6, v90
	v_min_u32_e32 v90, 0xd7fc0, v90
	v_mov_b32_e32 v91, 0
	s_add_u32 s16, s78, 0xfd200000
	s_addc_u32 s17, s79, -1
	v_lshl_add_u64 v[90:91], s[16:17], 0, v[90:91]
	global_load_dwordx4 v[92:95], v[90:91], off
	global_load_dwordx4 v[96:99], v[90:91], off offset:16
	global_load_dwordx4 v[100:103], v[90:91], off offset:32
	global_load_dwordx4 v[104:107], v[90:91], off offset:48
	v_mov_b32_e32 v80, v138
	v_mul_hi_i32 v2, v80, s39
	v_lshrrev_b32_e32 v3, 31, v2
	v_ashrrev_i32_e32 v2, 6, v2
	v_add_u32_e32 v50, v2, v3
	v_mul_i32_i24_e32 v9, 0x120, v50
	v_sub_u32_e32 v60, v80, v9
	v_add_u32_e32 v12, s35, v50
	v_mov_b64_e32 v[2:3], s[78:79]
	v_add_u32_e32 v4, 0x1200, v60
	v_mad_i64_i32 v[2:3], s[56:57], v12, s40, v[2:3]
	v_lshl_add_u64 v[2:3], v[4:5], 1, v[2:3]
	global_load_ushort v20, v[2:3], off
	v_add_co_u32_e32 v8, vcc, 0xffffd800, v2
	s_nop 1
	v_addc_co_u32_e32 v9, vcc, -1, v3, vcc
	global_load_ushort v30, v[8:9], off
	v_lshl_add_u64 v[8:9], v[4:5], 2, s[68:69]
	global_load_dword v40, v[8:9], off
	v_add_u32_e32 v81, 512, v138
	v_mul_hi_i32 v2, v81, s39
	v_lshrrev_b32_e32 v3, 31, v2
	v_ashrrev_i32_e32 v2, 6, v2
	v_add_u32_e32 v51, v2, v3
	v_mul_i32_i24_e32 v9, 0x120, v51
	v_sub_u32_e32 v61, v81, v9
	v_add_u32_e32 v12, s35, v51
	v_mov_b64_e32 v[2:3], s[78:79]
	v_add_u32_e32 v4, 0x1200, v61
	v_mad_i64_i32 v[2:3], s[56:57], v12, s40, v[2:3]
	v_lshl_add_u64 v[2:3], v[4:5], 1, v[2:3]
	global_load_ushort v21, v[2:3], off
	v_add_co_u32_e32 v8, vcc, 0xffffd800, v2
	s_nop 1
	v_addc_co_u32_e32 v9, vcc, -1, v3, vcc
	global_load_ushort v31, v[8:9], off
	v_lshl_add_u64 v[8:9], v[4:5], 2, s[68:69]
	global_load_dword v41, v[8:9], off
	v_add_u32_e32 v82, 1024, v138
	v_mul_hi_i32 v2, v82, s39
	v_lshrrev_b32_e32 v3, 31, v2
	v_ashrrev_i32_e32 v2, 6, v2
	v_add_u32_e32 v52, v2, v3
	v_mul_i32_i24_e32 v9, 0x120, v52
	v_sub_u32_e32 v62, v82, v9
	v_add_u32_e32 v12, s35, v52
	v_mov_b64_e32 v[2:3], s[78:79]
	v_add_u32_e32 v4, 0x1200, v62
	v_mad_i64_i32 v[2:3], s[56:57], v12, s40, v[2:3]
	v_lshl_add_u64 v[2:3], v[4:5], 1, v[2:3]
	global_load_ushort v22, v[2:3], off
	v_add_co_u32_e32 v8, vcc, 0xffffd800, v2
	s_nop 1
	v_addc_co_u32_e32 v9, vcc, -1, v3, vcc
	global_load_ushort v32, v[8:9], off
	v_lshl_add_u64 v[8:9], v[4:5], 2, s[68:69]
	global_load_dword v42, v[8:9], off
	v_add_u32_e32 v83, 1536, v138
	v_mul_hi_i32 v2, v83, s39
	v_lshrrev_b32_e32 v3, 31, v2
	v_ashrrev_i32_e32 v2, 6, v2
	v_add_u32_e32 v53, v2, v3
	v_mul_i32_i24_e32 v9, 0x120, v53
	v_sub_u32_e32 v63, v83, v9
	v_add_u32_e32 v12, s35, v53
	v_mov_b64_e32 v[2:3], s[78:79]
	v_add_u32_e32 v4, 0x1200, v63
	v_mad_i64_i32 v[2:3], s[56:57], v12, s40, v[2:3]
	v_lshl_add_u64 v[2:3], v[4:5], 1, v[2:3]
	global_load_ushort v23, v[2:3], off
	v_add_co_u32_e32 v8, vcc, 0xffffd800, v2
	s_nop 1
	v_addc_co_u32_e32 v9, vcc, -1, v3, vcc
	global_load_ushort v33, v[8:9], off
	v_lshl_add_u64 v[8:9], v[4:5], 2, s[68:69]
	global_load_dword v43, v[8:9], off
	v_add_u32_e32 v84, 2048, v138
	v_mul_hi_i32 v2, v84, s39
	v_lshrrev_b32_e32 v3, 31, v2
	v_ashrrev_i32_e32 v2, 6, v2
	v_add_u32_e32 v54, v2, v3
	v_mul_i32_i24_e32 v9, 0x120, v54
	v_sub_u32_e32 v64, v84, v9
	v_add_u32_e32 v12, s35, v54
	v_mov_b64_e32 v[2:3], s[78:79]
	v_add_u32_e32 v4, 0x1200, v64
	v_mad_i64_i32 v[2:3], s[56:57], v12, s40, v[2:3]
	v_lshl_add_u64 v[2:3], v[4:5], 1, v[2:3]
	global_load_ushort v24, v[2:3], off
	v_add_co_u32_e32 v8, vcc, 0xffffd800, v2
	s_nop 1
	v_addc_co_u32_e32 v9, vcc, -1, v3, vcc
	global_load_ushort v34, v[8:9], off
	v_lshl_add_u64 v[8:9], v[4:5], 2, s[68:69]
	global_load_dword v44, v[8:9], off
	v_add_u32_e32 v85, 2560, v138
	v_mul_hi_i32 v2, v85, s39
	v_lshrrev_b32_e32 v3, 31, v2
	v_ashrrev_i32_e32 v2, 6, v2
	v_add_u32_e32 v55, v2, v3
	v_mul_i32_i24_e32 v9, 0x120, v55
	v_sub_u32_e32 v65, v85, v9
	v_add_u32_e32 v12, s35, v55
	v_mov_b64_e32 v[2:3], s[78:79]
	v_add_u32_e32 v4, 0x1200, v65
	v_mad_i64_i32 v[2:3], s[56:57], v12, s40, v[2:3]
	v_lshl_add_u64 v[2:3], v[4:5], 1, v[2:3]
	global_load_ushort v25, v[2:3], off
	v_add_co_u32_e32 v8, vcc, 0xffffd800, v2
	s_nop 1
	v_addc_co_u32_e32 v9, vcc, -1, v3, vcc
	global_load_ushort v35, v[8:9], off
	v_lshl_add_u64 v[8:9], v[4:5], 2, s[68:69]
	global_load_dword v45, v[8:9], off
	v_add_u32_e32 v86, 3072, v138
	v_mul_hi_i32 v2, v86, s39
	v_lshrrev_b32_e32 v3, 31, v2
	v_ashrrev_i32_e32 v2, 6, v2
	v_add_u32_e32 v56, v2, v3
	v_mul_i32_i24_e32 v9, 0x120, v56
	v_sub_u32_e32 v66, v86, v9
	v_add_u32_e32 v12, s35, v56
	v_mov_b64_e32 v[2:3], s[78:79]
	v_add_u32_e32 v4, 0x1200, v66
	v_mad_i64_i32 v[2:3], s[56:57], v12, s40, v[2:3]
	v_lshl_add_u64 v[2:3], v[4:5], 1, v[2:3]
	global_load_ushort v26, v[2:3], off
	v_add_co_u32_e32 v8, vcc, 0xffffd800, v2
	s_nop 1
	v_addc_co_u32_e32 v9, vcc, -1, v3, vcc
	global_load_ushort v36, v[8:9], off
	v_lshl_add_u64 v[8:9], v[4:5], 2, s[68:69]
	global_load_dword v46, v[8:9], off
	v_add_u32_e32 v87, 3584, v138
	v_mul_hi_i32 v2, v87, s39
	v_lshrrev_b32_e32 v3, 31, v2
	v_ashrrev_i32_e32 v2, 6, v2
	v_add_u32_e32 v57, v2, v3
	v_mul_i32_i24_e32 v9, 0x120, v57
	v_sub_u32_e32 v67, v87, v9
	v_add_u32_e32 v12, s35, v57
	v_mov_b64_e32 v[2:3], s[78:79]
	v_add_u32_e32 v4, 0x1200, v67
	v_mad_i64_i32 v[2:3], s[56:57], v12, s40, v[2:3]
	v_lshl_add_u64 v[2:3], v[4:5], 1, v[2:3]
	global_load_ushort v27, v[2:3], off
	v_add_co_u32_e32 v8, vcc, 0xffffd800, v2
	s_nop 1
	v_addc_co_u32_e32 v9, vcc, -1, v3, vcc
	global_load_ushort v37, v[8:9], off
	v_lshl_add_u64 v[8:9], v[4:5], 2, s[68:69]
	global_load_dword v47, v[8:9], off
	v_add_u32_e32 v88, 4096, v138
	v_mul_hi_i32 v2, v88, s39
	v_lshrrev_b32_e32 v3, 31, v2
	v_ashrrev_i32_e32 v2, 6, v2
	v_add_u32_e32 v58, v2, v3
	v_mul_i32_i24_e32 v9, 0x120, v58
	v_sub_u32_e32 v68, v88, v9
	v_add_u32_e32 v12, s35, v58
	v_mov_b64_e32 v[2:3], s[78:79]
	v_add_u32_e32 v4, 0x1200, v68
	v_mad_i64_i32 v[2:3], s[56:57], v12, s40, v[2:3]
	v_lshl_add_u64 v[2:3], v[4:5], 1, v[2:3]
	global_load_ushort v28, v[2:3], off
	v_add_co_u32_e32 v8, vcc, 0xffffd800, v2
	s_nop 1
	v_addc_co_u32_e32 v9, vcc, -1, v3, vcc
	global_load_ushort v38, v[8:9], off
	v_lshl_add_u64 v[8:9], v[4:5], 2, s[68:69]
	global_load_dword v48, v[8:9], off
	s_cmp_lg_u32 s9, 0
	s_cbranch_scc1 .Lb1s_nosp_ld
	v_readlane_b32 s20, v255, 41
	v_readlane_b32 s21, v255, 42
	s_cmp_eq_u64 s[20:21], 0
	s_cbranch_scc1 .Lb1s_nosp_ld
	v_cmp_eq_u32_e32 vcc, 0, v50
	s_and_saveexec_b64 s[16:17], vcc
	v_add_u32_e32 v4, 0x1200, v60
	v_lshl_add_u64 v[2:3], v[4:5], 1, s[14:15]
	global_load_ushort v70, v[2:3], off
	s_mov_b64 exec, s[16:17]
